# M2 task split changed: scan-long workgroups take 3 short tasks each, the 64 short-task workgroups 15 each (was 2 / 18)
# baseline (speedup 1.0000x reference)
; DI void phase_m2(LAS unsigned char* lds, const Params& P, int l) {
;     ...
;     if (G == 256) {
;         if (g < 192) {
;             const int x = g & 7, j = g >> 3; scan_long(lds, P, l, (x + 8 * (j >> 2)) * 4 + (j & 3)); __syncthreads();
; #pragma clang loop unroll(disable)
;             for (int j = 0; j < 2; ++j) scan_short(lds, P, l, 1152 + g * 2 + j); }
;         else {
; #pragma clang loop unroll(disable)
;             for (int j = 0; j < 18; ++j) scan_short(lds, P, l, (g - 192) * 18 + j); }
.LBB0_1324:
	s_and_b64 vcc, exec, s[0:1]
	s_cbranch_vccz .LBB0_1412
	v_readlane_b32 s0, v253, 33
	v_readlane_b32 s1, v253, 34
	s_andn2_b64 vcc, exec, s[0:1]
	s_mov_b64 s[0:1], -1
	s_cbranch_vccnz .LBB0_1359
	v_readlane_b32 s0, v250, 49
	s_lshl_b32 s4, s0, 9
	s_movk_i32 s5, 0xfff1
	v_readlane_b32 s1, v250, 50
	s_branch .LBB0_1329

; #define LAS __attribute__((address_space(3)))
; template <int KT, bool HASW>
; DI void scan_sample_wave(LAS unsigned char* ldsw, const ScanBufs B, int unit, const float* vsrc  , const float* s0, float* sout, float* oraw  , int nt, int lane) {
;     const int r = lane & 15, q = lane >> 4;
;     constexpr int K = KT * 16, LDK = K + 8, LDD = 40;
;     LAS bf16_t* ST = (LAS bf16_t*)ldsw; LAS bf16_t* DT = ST + 16 * LDK;
;     const size_t un = (size_t)unit;
;     const bf16_t* qg = B.qg + un * 64 * K; const bf16_t* kd = B.kd + un * 64 * K; const bf16_t* qk = B.qk + un * 64 * 64; const float* Dv = B.D + un * K;
;     f32x4 S[KT], Dr[KT]; bf16x8 a_kd[KT], a_qg[K / 32], a_w[K / 32], a_qk; float uu[4];
; #pragma unroll
;     for (int kt = 0; kt < KT; ++kt) {
; #pragma unroll
;         for (int j = 0; j < 4; ++j) S[kt][j] = s0[(size_t)(kt * 16 + 4 * q + j) * 128 + nt * 16 + r]; }
;     if (HASW) { const bf16_t* wb = B.w + un * 64 * 128; const float* ub = B.u + un * 64 * 128;
; #pragma unroll
;         for (int kk = 0; kk < K / 32; ++kk) a_w[kk] = *(const bf16x8*)(wb + r * 128 + kk * 32 + 8 * q);
; #pragma unroll
;         for (int j = 0; j < 4; ++j) uu[j] = ub[(4 * q + j) * 128 + nt * 16 + r]; }
;     else {
; #pragma unroll
;         for (int j = 0; j < 4; ++j) uu[j] = (q == 0) ? vsrc[(size_t)j * LDP + nt * 16 + r] : 0.f; }
; #pragma unroll
;     for (int kk = 0; kk < K / 32; ++kk) a_qg[kk] = *(const bf16x8*)(qg + r * K + kk * 32 + 8 * q);
;     a_qk = *(const bf16x8*)(qk + r * 64 + 8 * q);
; #pragma unroll
;     for (int kt = 0; kt < KT; ++kt) { a_kd[kt] = *(const bf16x8*)(kd + (kt * 16 + r) * 64 + 8 * q); Dr[kt] = *(const f32x4*)(Dv + kt * 16 + 4 * q); }
; DI void scan_short(LAS unsigned char* lds, const Params& P, int l, int T) {
;     const int tid = ltid(), wave = __builtin_amdgcn_readfirstlane(tid >> 6), lane = tid & 63;
;     const int mixer = T / 512, bh = T % 512, b = bh >> 2, h = bh & 3;
;     LAS unsigned char* ldsw = lds + wave * 6144;
;     const float* P32 = (const float*)(lwsp(P) + lo(WS_P32));
;     float* oraw = (float*)(lwsp(P) + lo(WS_ORAW)) + (size_t)mixer * MT * 512 + (size_t)(MPR + b * 4) * 512 + h * 128;
;     const int unit = 512 + bh;
;     if (mixer == 0) { ScanBufs B{(const bf16_t*)(lwsp(P) + lo(PB_QG)), (const bf16_t*)(lwsp(P) + lo(PB_KD)), (const bf16_t*)(lwsp(P) + lo(PB_QK)), (const float*)(lwsp(P) + lo(PB_D)), nullptr, nullptr};
.LBB0_1329:
	v_readlane_b32 s0, v250, 24
	s_mul_i32 s0, s0, 15
	v_readlane_b32 s1, v250, 25
	s_add_i32 s16, s0, s5
	v_mov_b32_e32 v191, v197
	s_add_i32 s1, s16, 0xfffff4cf
	s_mov_b64 s[2:3], 0x10060000
	v_readfirstlane_b32 s0, v191
	s_ashr_i32 s9, s0, 6
	s_ashr_i32 s0, s1, 31
	s_lshr_b32 s0, s0, 23
	s_add_i32 s0, s1, s0
	s_ashr_i32 s6, s0, 9
	s_and_b32 s0, s0, 0xfffffe00
	s_sub_i32 s15, s1, s0
	s_mul_i32 s0, s9, 0x1800
	s_and_b32 s10, s15, 3
	s_add_i32 s8, s0, 0
	s_add_u32 s12, s92, s2
	s_addc_u32 s13, s93, s3
	s_mov_b64 s[2:3], 0x30720000
	s_add_u32 s0, s92, s2
	s_addc_u32 s2, s93, s3
	s_mul_hi_i32 s3, s6, 0x1100000
	s_mul_i32 s6, s6, 0x1100000
	s_add_u32 s0, s0, s6
	s_addc_u32 s6, s2, s3
	s_and_b32 s11, s15, -4
	s_add_i32 s28, s11, 0x2000
	s_lshl_b64 s[2:3], s[28:29], 11
	s_add_u32 s0, s0, s2
	s_addc_u32 s2, s6, s3
	s_lshl_b32 s14, s10, 7
	s_lshl_b32 s3, s10, 9
	s_add_u32 s6, s0, s3
	s_addc_u32 s7, s2, 0
	s_add_i32 s0, s15, 0x200
	s_addk_i32 s16, 0xf6ce
	v_and_b32_e32 v190, 63, v191
	s_cmpk_gt_u32 s16, 0x3fe
	s_mov_b64 s[2:3], -1
	s_cbranch_scc0 .LBB0_1346
	s_and_b32 s1, s1, 0xfffffe00
	s_cmpk_lg_i32 s1, 0x200
	s_cbranch_scc0 .LBB0_1334
	s_mov_b64 s[2:3], 0x2aea0000
	s_add_u32 s18, s92, s2
	s_addc_u32 s19, s93, s3
	s_mov_b64 s[2:3], 0x2bea0000
	s_add_u32 s40, s92, s2
	s_addc_u32 s41, s93, s3
	s_mov_b64 s[2:3], 0x2cea0000
	s_add_u32 s54, s92, s2
	s_addc_u32 s55, s93, s3
	s_mov_b64 s[2:3], 0x2d6a0000
	s_add_u32 s16, s92, s2
	s_addc_u32 s17, s93, s3
	s_mov_b64 s[2:3], 0x2d720000
	s_add_u32 s56, s92, s2
	s_addc_u32 s57, s93, s3
	s_mov_b64 s[2:3], 0x2e720000
	s_add_u32 s52, s92, s2
	s_addc_u32 s53, s93, s3
	s_mov_b64 s[2:3], 0
	v_readlane_b32 s60, v251, 2
	s_lshl_b64 s[2:3], s[2:3], 2
	v_readlane_b32 s68, v251, 10
	v_readlane_b32 s69, v251, 11
	s_add_u32 s1, s68, s2
	s_addc_u32 s42, s69, s3
	s_add_i32 s2, s11, s4
	s_or_b32 s2, s2, s10
	s_ashr_i32 s3, s2, 31
	s_lshl_b64 s[30:31], s[2:3], 16
	s_add_u32 s58, s1, s30
	s_mov_b32 s1, s29
	s_addc_u32 s59, s42, s31
	s_lshl_b64 s[50:51], s[0:1], 13
	s_lshl_b64 s[48:49], s[0:1], 14
	s_add_u32 s42, s40, s48
	s_addc_u32 s43, s41, s49
	s_lshl_b32 s46, s9, 4
	s_ashr_i32 s47, s46, 31
	s_lshl_b64 s[44:45], s[0:1], 9
	s_lshl_b64 s[40:41], s[46:47], 2
	v_and_b32_e32 v193, 15, v191
	s_add_u32 s58, s58, s40
	v_lshrrev_b32_e32 v8, 4, v190
	s_addc_u32 s59, s59, s41
	v_lshlrev_b32_e32 v0, 2, v193
	v_lshl_add_u64 v[2:3], s[58:59], 0, v[0:1]
	v_lshlrev_b32_e32 v4, 11, v8
	v_mov_b32_e32 v5, v1
	s_mov_b64 s[30:31], 0
	v_lshlrev_b32_e32 v192, 9, v8
	v_lshl_add_u64 v[4:5], v[2:3], 0, v[4:5]
	global_load_dword v100, v[4:5], off
	global_load_dword v101, v[4:5], off offset:512
	global_load_dword v104, v[4:5], off offset:1024
	global_load_dword v105, v[4:5], off offset:1536
	v_or_b32_e32 v4, 0x800, v192
	v_lshlrev_b32_e32 v98, 2, v4
	v_mov_b32_e32 v99, v1
	v_lshl_add_u64 v[4:5], v[2:3], 0, v[98:99]
	global_load_dword v106, v[4:5], off
	v_or_b32_e32 v4, 0x880, v192
	v_lshlrev_b32_e32 v102, 2, v4
	v_mov_b32_e32 v103, v1
	v_lshl_add_u64 v[4:5], v[2:3], 0, v[102:103]
	global_load_dword v107, v[4:5], off
	v_or_b32_e32 v4, 0x900, v192
	v_lshlrev_b32_e32 v108, 2, v4
	v_mov_b32_e32 v109, v1
	v_lshl_add_u64 v[4:5], v[2:3], 0, v[108:109]
	global_load_dword v112, v[4:5], off
	v_or_b32_e32 v4, 0x980, v192
	v_lshlrev_b32_e32 v110, 2, v4
	v_mov_b32_e32 v111, v1
	v_lshl_add_u64 v[4:5], v[2:3], 0, v[110:111]
	global_load_dword v113, v[4:5], off
	v_or_b32_e32 v4, 0x1000, v192
	v_lshlrev_b32_e32 v114, 2, v4
	v_mov_b32_e32 v115, v1
	v_lshl_add_u64 v[4:5], v[2:3], 0, v[114:115]
	global_load_dword v118, v[4:5], off
	v_or_b32_e32 v4, 0x1080, v192
	v_lshlrev_b32_e32 v116, 2, v4
	v_mov_b32_e32 v117, v1
	v_lshl_add_u64 v[4:5], v[2:3], 0, v[116:117]
	global_load_dword v119, v[4:5], off
	v_or_b32_e32 v4, 0x1100, v192
	v_lshlrev_b32_e32 v120, 2, v4
	v_mov_b32_e32 v121, v1
	v_lshl_add_u64 v[4:5], v[2:3], 0, v[120:121]
	global_load_dword v130, v[4:5], off
	v_or_b32_e32 v4, 0x1180, v192
	v_lshlrev_b32_e32 v124, 2, v4
	v_mov_b32_e32 v125, v1
	v_lshl_add_u64 v[4:5], v[2:3], 0, v[124:125]
	global_load_dword v131, v[4:5], off
	v_or_b32_e32 v4, 0x1800, v192
	v_lshlrev_b32_e32 v122, 2, v4
	v_mov_b32_e32 v123, v1
	v_lshl_add_u64 v[4:5], v[2:3], 0, v[122:123]
	global_load_dword v128, v[4:5], off
	v_or_b32_e32 v4, 0x1880, v192
	v_lshlrev_b32_e32 v126, 2, v4
	v_mov_b32_e32 v127, v1
	v_lshl_add_u64 v[4:5], v[2:3], 0, v[126:127]
	global_load_dword v129, v[4:5], off
	v_or_b32_e32 v4, 0x1900, v192
	v_lshlrev_b32_e32 v132, 2, v4
	v_mov_b32_e32 v133, v1
	v_lshl_add_u64 v[4:5], v[2:3], 0, v[132:133]
	global_load_dword v136, v[4:5], off
	v_or_b32_e32 v4, 0x1980, v192
	v_lshlrev_b32_e32 v134, 2, v4
	v_mov_b32_e32 v135, v1
	v_lshl_add_u64 v[4:5], v[2:3], 0, v[134:135]
	global_load_dword v137, v[4:5], off
	v_or_b32_e32 v4, 0x2000, v192
	v_lshlrev_b32_e32 v138, 2, v4
	v_mov_b32_e32 v139, v1
	v_lshl_add_u64 v[4:5], v[2:3], 0, v[138:139]
	global_load_dword v142, v[4:5], off
	v_or_b32_e32 v4, 0x2080, v192
	v_lshlrev_b32_e32 v140, 2, v4
	v_mov_b32_e32 v141, v1
	v_lshl_add_u64 v[4:5], v[2:3], 0, v[140:141]
	global_load_dword v143, v[4:5], off
	v_or_b32_e32 v4, 0x2100, v192
	v_lshlrev_b32_e32 v144, 2, v4
	v_mov_b32_e32 v145, v1
	v_lshl_add_u64 v[4:5], v[2:3], 0, v[144:145]
	global_load_dword v154, v[4:5], off
	v_or_b32_e32 v4, 0x2180, v192
	v_lshlrev_b32_e32 v148, 2, v4
	v_mov_b32_e32 v149, v1
	v_lshl_add_u64 v[4:5], v[2:3], 0, v[148:149]
	global_load_dword v155, v[4:5], off
	v_or_b32_e32 v4, 0x2800, v192
	v_lshlrev_b32_e32 v146, 2, v4
	v_mov_b32_e32 v147, v1
	v_lshl_add_u64 v[4:5], v[2:3], 0, v[146:147]
	global_load_dword v152, v[4:5], off
	v_or_b32_e32 v4, 0x2880, v192
; template <int KT, bool HASW>
; DI void scan_sample_wave(LAS unsigned char* ldsw, const ScanBufs B, int unit, const float* vsrc  , const float* s0, float* sout, float* oraw  , int nt, int lane) {
;     ...
; #pragma unroll
;     for (int kt = 0; kt < KT; ++kt) {
; #pragma unroll
;         for (int j = 0; j < 4; ++j) S[kt][j] = s0[(size_t)(kt * 16 + 4 * q + j) * 128 + nt * 16 + r]; }
;     if (HASW) { const bf16_t* wb = B.w + un * 64 * 128; const float* ub = B.u + un * 64 * 128;
; #pragma unroll
;         for (int kk = 0; kk < K / 32; ++kk) a_w[kk] = *(const bf16x8*)(wb + r * 128 + kk * 32 + 8 * q);
; #pragma unroll
;         for (int j = 0; j < 4; ++j) uu[j] = ub[(4 * q + j) * 128 + nt * 16 + r]; }
;     else {
; #pragma unroll
;         for (int j = 0; j < 4; ++j) uu[j] = (q == 0) ? vsrc[(size_t)j * LDP + nt * 16 + r] : 0.f; }
; #pragma unroll
;     for (int kk = 0; kk < K / 32; ++kk) a_qg[kk] = *(const bf16x8*)(qg + r * K + kk * 32 + 8 * q);
;     a_qk = *(const bf16x8*)(qk + r * 64 + 8 * q);
; #pragma unroll
;     for (int kt = 0; kt < KT; ++kt) { a_kd[kt] = *(const bf16x8*)(kd + (kt * 16 + r) * 64 + 8 * q); Dr[kt] = *(const f32x4*)(Dv + kt * 16 + 4 * q); }
	v_lshlrev_b32_e32 v150, 2, v4
	v_mov_b32_e32 v151, v1
	v_lshl_add_u64 v[4:5], v[2:3], 0, v[150:151]
	global_load_dword v153, v[4:5], off
	v_or_b32_e32 v4, 0x2900, v192
	v_lshlrev_b32_e32 v156, 2, v4
	v_mov_b32_e32 v157, v1
	v_lshl_add_u64 v[4:5], v[2:3], 0, v[156:157]
	global_load_dword v160, v[4:5], off
	v_or_b32_e32 v4, 0x2980, v192
	v_lshlrev_b32_e32 v158, 2, v4
	v_mov_b32_e32 v159, v1
	v_lshl_add_u64 v[4:5], v[2:3], 0, v[158:159]
	global_load_dword v161, v[4:5], off
	v_or_b32_e32 v4, 0x3000, v192
	v_lshlrev_b32_e32 v162, 2, v4
	v_mov_b32_e32 v163, v1
	v_lshl_add_u64 v[4:5], v[2:3], 0, v[162:163]
	global_load_dword v166, v[4:5], off
	v_or_b32_e32 v4, 0x3080, v192
	v_lshlrev_b32_e32 v164, 2, v4
	v_mov_b32_e32 v165, v1
	v_lshl_add_u64 v[4:5], v[2:3], 0, v[164:165]
	global_load_dword v167, v[4:5], off
	v_or_b32_e32 v4, 0x3100, v192
	v_lshlrev_b32_e32 v168, 2, v4
	v_mov_b32_e32 v169, v1
	v_lshl_add_u64 v[4:5], v[2:3], 0, v[168:169]
	global_load_dword v178, v[4:5], off
	v_or_b32_e32 v4, 0x3180, v192
	v_lshlrev_b32_e32 v172, 2, v4
	v_mov_b32_e32 v173, v1
	v_lshl_add_u64 v[4:5], v[2:3], 0, v[172:173]
	global_load_dword v179, v[4:5], off
	v_or_b32_e32 v4, 0x3800, v192
	v_lshlrev_b32_e32 v170, 2, v4
	v_mov_b32_e32 v171, v1
	v_lshl_add_u64 v[4:5], v[2:3], 0, v[170:171]
	global_load_dword v176, v[4:5], off
	v_or_b32_e32 v4, 0x3880, v192
	v_lshlrev_b32_e32 v174, 2, v4
	v_mov_b32_e32 v175, v1
	v_lshl_add_u64 v[4:5], v[2:3], 0, v[174:175]
	global_load_dword v177, v[4:5], off
	v_or_b32_e32 v4, 0x3900, v192
	v_lshlrev_b32_e32 v180, 2, v4
	v_mov_b32_e32 v181, v1
	v_lshl_add_u64 v[4:5], v[2:3], 0, v[180:181]
	global_load_dword v184, v[4:5], off
	v_or_b32_e32 v4, 0x3980, v192
	v_lshlrev_b32_e32 v182, 2, v4
	v_mov_b32_e32 v183, v1
	v_lshl_add_u64 v[2:3], v[2:3], 0, v[182:183]
	global_load_dword v185, v[2:3], off
	s_add_u32 s50, s54, s50
	s_addc_u32 s51, s55, s51
	s_add_u32 s54, s56, s48
	s_addc_u32 s55, s57, s49
	v_lshlrev_b32_e32 v4, 8, v193
	v_mov_b32_e32 v5, v1
	v_lshl_add_u64 v[6:7], s[54:55], 0, v[4:5]
	v_and_b32_e32 v14, 48, v190
	v_mov_b32_e32 v15, v1
	v_lshl_add_u64 v[6:7], v[6:7], 0, v[14:15]
	global_load_dwordx4 v[90:93], v[6:7], off
	global_load_dwordx4 v[206:209], v[6:7], off offset:64
	global_load_dwordx4 v[94:97], v[6:7], off offset:128
	global_load_dwordx4 v[86:89], v[6:7], off offset:192
	s_add_u32 s18, s18, s48
	s_addc_u32 s19, s19, s49
	s_lshl_b64 s[48:49], s[0:1], 15
	v_or_b32_e32 v6, s46, v193
	s_add_u32 s48, s52, s48
	v_add_u32_e32 v6, v6, v192
	s_addc_u32 s49, s53, s49
	v_ashrrev_i32_e32 v7, 31, v6
	v_lshl_add_u64 v[6:7], v[6:7], 2, s[48:49]
	global_load_dword v188, v[6:7], off
	global_load_dword v189, v[6:7], off offset:512
	global_load_dword v186, v[6:7], off offset:1024
	global_load_dword v187, v[6:7], off offset:1536
	v_lshl_add_u64 v[4:5], s[18:19], 0, v[4:5]
	v_lshl_add_u64 v[4:5], v[4:5], 0, v[14:15]
	global_load_dwordx4 v[82:85], v[4:5], off
	global_load_dwordx4 v[78:81], v[4:5], off offset:64
	global_load_dwordx4 v[74:77], v[4:5], off offset:128
	global_load_dwordx4 v[66:69], v[4:5], off offset:192
	v_lshlrev_b32_e32 v2, 7, v193
	v_mov_b32_e32 v3, v1
	v_lshl_add_u64 v[4:5], s[50:51], 0, v[2:3]
	v_lshl_add_u64 v[4:5], v[4:5], 0, v[14:15]
	global_load_dwordx4 v[70:73], v[4:5], off
	v_lshl_add_u64 v[6:7], s[42:43], 0, v[14:15]
	v_lshl_add_u64 v[2:3], v[6:7], 0, v[2:3]
	v_lshlrev_b32_e32 v15, 7, v190
	v_lshlrev_b32_e32 v199, 3, v8
	v_add_co_u32_e32 v4, vcc, s86, v2
	v_or_b32_e32 v8, 0x1800, v15
	v_mov_b32_e32 v9, v1
	s_add_u32 s16, s16, s44
	v_addc_co_u32_e32 v5, vcc, 0, v3, vcc
	v_lshl_add_u64 v[8:9], v[6:7], 0, v[8:9]
	s_addc_u32 s17, s17, s45
	global_load_dwordx4 v[58:61], v[2:3], off
	global_load_dwordx4 v[62:65], v14, s[16:17]
	global_load_dwordx4 v[46:49], v[2:3], off offset:2048
	global_load_dwordx4 v[54:57], v14, s[16:17] offset:64
	global_load_dwordx4 v[34:37], v[4:5], off offset:-4096
	global_load_dwordx4 v[42:45], v14, s[16:17] offset:128
	global_load_dwordx4 v[38:41], v[8:9], off
	global_load_dwordx4 v[50:53], v14, s[16:17] offset:192
	global_load_dwordx4 v[26:29], v[4:5], off
	global_load_dwordx4 v[30:33], v14, s[16:17] offset:256
	global_load_dwordx4 v[18:21], v[4:5], off offset:2048
	global_load_dwordx4 v[22:25], v14, s[16:17] offset:320
	s_movk_i32 s1, 0x3000
	v_add_co_u32_e32 v2, vcc, s1, v2
	v_or_b32_e32 v8, 0x3800, v15
	v_mov_b32_e32 v9, v1
	v_addc_co_u32_e32 v3, vcc, 0, v3, vcc
	v_lshl_add_u64 v[6:7], v[6:7], 0, v[8:9]
	global_load_dwordx4 v[2:5], v[2:3], off
	s_nop 0
	global_load_dwordx4 v[10:13], v14, s[16:17] offset:384
	s_nop 0
	global_load_dwordx4 v[6:9], v[6:7], off
	s_nop 0
	global_load_dwordx4 v[14:17], v14, s[16:17] offset:448
	v_mul_u32_u24_e32 v200, 0x110, v193
	v_add3_u32 v200, s8, v200, v199
	s_waitcnt vmcnt(59)
; #define LAS __attribute__((address_space(3)))
; DI unsigned pk2(float lo, float hi) { const f32x2 v = {lo, hi}; return __builtin_bit_cast(unsigned, __builtin_convertvector(v, bf16n2)); }
; DI f32x4 mfma16(bf16x8 a, bf16x8 b, f32x4 c) { return __builtin_amdgcn_mfma_f32_16x16x32_bf16(a, b, c, 0, 0, 0); }
; template <int KT, bool HASW>
; DI void scan_sample_wave(LAS unsigned char* ldsw, const ScanBufs B, int unit, const float* vsrc  , const float* s0, float* sout, float* oraw  , int nt, int lane) {
;     ...
;     for (int kt = 0; kt < KT; ++kt) { u32x2 w; w.x = pk2(S[kt][0], S[kt][1]); w.y = pk2(S[kt][2], S[kt][3]); *(LAS u32x2*)(ST + r * LDK + kt * 16 + 4 * q) = w; }
;     f32x4 acc = {0.f, 0.f, 0.f, 0.f};
;     if (HASW) {
; #pragma unroll
;         for (int kk = 0; kk < K / 32; ++kk) { const bf16x8 b = *(const LAS bf16x8*)(ST + r * LDK + kk * 32 + 8 * q); acc = mfma16(a_w[kk], b, acc); } }
;     { u32x2 w; w.x = pk2(uu[0] - acc[0], uu[1] - acc[1]); w.y = pk2(uu[2] - acc[2], uu[3] - acc[3]); *(LAS u32x2*)(DT + r * LDD + 4 * q) = w;
;       unsigned vz = 0; asm volatile("" : "+v"(vz)); u32x2 z; z.x = vz; z.y = vz; *(LAS u32x2*)(DT + r * LDD + 16 + 4 * q) = z; }
;     const bf16x8 bd = *(const LAS bf16x8*)(DT + r * LDD + 8 * q);
;     acc = (f32x4){0.f, 0.f, 0.f, 0.f};
; #pragma unroll
;     for (int kk = 0; kk < K / 32; ++kk) { const bf16x8 b = *(const LAS bf16x8*)(ST + r * LDK + kk * 32 + 8 * q); acc = mfma16(a_qg[kk], b, acc); }
;     acc = mfma16(a_qk, bd, acc);
;     if (q == 0) {
; #pragma unroll
;         for (int j = 0; j < 4; ++j) oraw[(size_t)j * 512 + nt * 16 + r] = acc[j]; }
	v_cvt_pk_bf16_f32 v210, v100, v101
	s_waitcnt vmcnt(57)
	v_cvt_pk_bf16_f32 v211, v104, v105
	s_waitcnt vmcnt(55)
	v_cvt_pk_bf16_f32 v212, v106, v107
	s_waitcnt vmcnt(53)
	v_cvt_pk_bf16_f32 v213, v112, v113
	ds_write2_b64 v200, v[210:211], v[212:213] offset1:4
	s_waitcnt vmcnt(51)
	v_cvt_pk_bf16_f32 v210, v118, v119
	s_waitcnt vmcnt(49)
	v_cvt_pk_bf16_f32 v211, v130, v131
	s_waitcnt vmcnt(47)
	v_cvt_pk_bf16_f32 v212, v128, v129
	s_waitcnt vmcnt(45)
	v_cvt_pk_bf16_f32 v213, v136, v137
	ds_write2_b64 v200, v[210:211], v[212:213] offset0:8 offset1:12
	s_waitcnt vmcnt(43)
	v_cvt_pk_bf16_f32 v210, v142, v143
	s_waitcnt vmcnt(41)
	v_cvt_pk_bf16_f32 v211, v154, v155
	s_waitcnt vmcnt(39)
	v_cvt_pk_bf16_f32 v212, v152, v153
	s_waitcnt vmcnt(37)
	v_cvt_pk_bf16_f32 v213, v160, v161
	ds_write2_b64 v200, v[210:211], v[212:213] offset0:16 offset1:20
	s_waitcnt vmcnt(35)
	v_cvt_pk_bf16_f32 v210, v166, v167
	s_waitcnt vmcnt(33)
	v_cvt_pk_bf16_f32 v211, v178, v179
	s_waitcnt vmcnt(31)
	v_cvt_pk_bf16_f32 v212, v176, v177
	v_cmp_gt_u32_e32 vcc, 16, v190
	v_readlane_b32 s61, v251, 3
	v_readlane_b32 s62, v251, 4
	v_readlane_b32 s63, v251, 5
	s_waitcnt vmcnt(29)
	v_cvt_pk_bf16_f32 v213, v184, v185
	ds_write2_b64 v200, v[210:211], v[212:213] offset0:24 offset1:28
	v_add_u32_e32 v200, v200, v199
	ds_read_b128 v[210:213], v200
	s_waitcnt vmcnt(28) lgkmcnt(0)
	v_mfma_f32_16x16x32_bf16 v[90:93], v[90:93], v[210:213], 0
	ds_read_b128 v[210:213], v200 offset:64
	v_readlane_b32 s64, v251, 6
	v_readlane_b32 s65, v251, 7
	s_waitcnt vmcnt(27) lgkmcnt(0)
	v_mfma_f32_16x16x32_bf16 v[90:93], v[206:209], v[210:213], v[90:93]
	ds_read_b128 v[206:209], v200 offset:128
	v_readlane_b32 s66, v251, 8
	v_readlane_b32 s67, v251, 9
	s_waitcnt vmcnt(26) lgkmcnt(0)
	v_mfma_f32_16x16x32_bf16 v[90:93], v[94:97], v[206:209], v[90:93]
	ds_read_b128 v[94:97], v200 offset:192
	v_readlane_b32 s70, v251, 12
	v_readlane_b32 s71, v251, 13
	s_waitcnt vmcnt(25) lgkmcnt(0)
	v_mfma_f32_16x16x32_bf16 v[86:89], v[86:89], v[94:97], v[90:93]
	v_readlane_b32 s72, v251, 14
	v_readlane_b32 s73, v251, 15
	v_readlane_b32 s74, v251, 16
	s_waitcnt vmcnt(23)
	s_nop 3
	v_pk_add_f32 v[86:87], v[188:189], v[86:87] neg_lo:[0,1] neg_hi:[0,1]
	s_waitcnt vmcnt(21)
	v_pk_add_f32 v[88:89], v[186:187], v[88:89] neg_lo:[0,1] neg_hi:[0,1]
	v_cvt_pk_bf16_f32 v86, v86, v87
	v_cvt_pk_bf16_f32 v87, v88, v89
	v_mul_u32_u24_e32 v88, 0x50, v193
	v_add3_u32 v88, s8, v88, v199
	ds_write_b64 v88, v[86:87] offset:4352
	v_mov_b32_e32 v86, v1
	v_readlane_b32 s75, v251, 17
	v_mov_b32_e32 v87, v86
	ds_write_b64 v88, v[86:87] offset:4384
	v_add_u32_e32 v86, v88, v199
	ds_read_b128 v[86:89], v86 offset:4352
	ds_read_b128 v[90:93], v200
	s_waitcnt vmcnt(20) lgkmcnt(0)
	v_mfma_f32_16x16x32_bf16 v[82:85], v[82:85], v[90:93], 0
	ds_read_b128 v[90:93], v200 offset:64
	s_waitcnt vmcnt(19) lgkmcnt(0)
	v_mfma_f32_16x16x32_bf16 v[78:81], v[78:81], v[90:93], v[82:85]
	s_nop 4
	ds_read_b128 v[82:85], v200 offset:128
	s_waitcnt vmcnt(18) lgkmcnt(0)
	v_mfma_f32_16x16x32_bf16 v[74:77], v[74:77], v[82:85], v[78:81]
	s_nop 2
	ds_read_b128 v[78:81], v200 offset:192
	s_waitcnt vmcnt(17) lgkmcnt(0)
	v_mfma_f32_16x16x32_bf16 v[66:69], v[66:69], v[78:81], v[74:77]
	s_waitcnt vmcnt(16)
	v_mfma_f32_16x16x32_bf16 v[66:69], v[70:73], v[86:89], v[66:69]
	s_and_saveexec_b64 s[42:43], vcc
	s_cbranch_execz .LBB0_1333
	s_add_u32 s16, s6, s40
	s_addc_u32 s17, s7, s41
	v_lshlrev_b32_e32 v70, 2, v190
	v_mov_b32_e32 v71, v1
	v_lshl_add_u64 v[72:73], s[16:17], 0, v[70:71]
	s_nop 0
	global_store_dword v70, v66, s[16:17]
	global_store_dword v70, v67, s[16:17] offset:2048
	v_add_co_u32_e32 v66, vcc, 0x1000, v72
	s_nop 1
	v_addc_co_u32_e32 v67, vcc, 0, v73, vcc
	global_store_dword v[66:67], v68, off
	global_store_dword v[66:67], v69, off offset:2048

; template <int KT, bool HASW>
; DI void scan_long_task(LAS unsigned char* lds, const ScanBufs B, int unit0, const float* vsrc  , float* sout, float* oraw  , int v0) {
;     ...
;     for (int i = 0; i < NS; ++i) { const int id = wave + 8 * i, kt = id % KT, nt = id / KT;
; #pragma unroll
;         for (int j = 0; j < 4; ++j) sout[(size_t)(kt * 16 + 4 * q + j) * 128 + v0 + nt * 16 + r] = S[i][j]; }
; DI void phase_m2(LAS unsigned char* lds, const Params& P, int l) {
;     ...
;             const int x = g & 7, j = g >> 3; scan_long(lds, P, l, (x + 8 * (j >> 2)) * 4 + (j & 3)); __syncthreads();
; #pragma clang loop unroll(disable)
;             for (int j = 0; j < 2; ++j) scan_short(lds, P, l, 1152 + g * 2 + j); }
.LBB0_1380:
	v_ashrrev_i32_e32 v7, 31, v6
	v_lshlrev_b64 v[10:11], 9, v[6:7]
	v_lshl_add_u64 v[10:11], v[8:9], 0, v[10:11]
	global_store_dword v[10:11], v2, off
	v_or_b32_e32 v10, 1, v6
	v_ashrrev_i32_e32 v11, 31, v10
	v_lshlrev_b64 v[10:11], 9, v[10:11]
	v_lshl_add_u64 v[10:11], v[8:9], 0, v[10:11]
	v_or_b32_e32 v2, 2, v6
	global_store_dword v[10:11], v3, off
	v_ashrrev_i32_e32 v3, 31, v2
	v_lshlrev_b64 v[2:3], 9, v[2:3]
	v_lshl_add_u64 v[2:3], v[8:9], 0, v[2:3]
	global_store_dword v[2:3], v4, off
	v_or_b32_e32 v2, 3, v6
	v_ashrrev_i32_e32 v3, 31, v2
	v_readlane_b32 s0, v250, 49
	v_lshlrev_b64 v[2:3], 9, v[2:3]
	v_readlane_b32 s1, v250, 50
	v_lshl_add_u64 v[2:3], v[8:9], 0, v[2:3]
	s_lshl_b32 s4, s0, 9
	s_mov_b32 s2, 0
	s_mov_b32 s82, 0
	s_mov_b64 s[0:1], -1
	global_store_dword v[2:3], v5, off
	s_waitcnt lgkmcnt(0)
	s_barrier
	s_branch .LBB0_1383

; #define LAS __attribute__((address_space(3)))
; template <int KT, bool HASW>
; DI void scan_sample_wave(LAS unsigned char* ldsw, const ScanBufs B, int unit, const float* vsrc  , const float* s0, float* sout, float* oraw  , int nt, int lane) {
;     const int r = lane & 15, q = lane >> 4;
;     constexpr int K = KT * 16, LDK = K + 8, LDD = 40;
;     LAS bf16_t* ST = (LAS bf16_t*)ldsw; LAS bf16_t* DT = ST + 16 * LDK;
;     const size_t un = (size_t)unit;
;     const bf16_t* qg = B.qg + un * 64 * K; const bf16_t* kd = B.kd + un * 64 * K; const bf16_t* qk = B.qk + un * 64 * 64; const float* Dv = B.D + un * K;
;     f32x4 S[KT], Dr[KT]; bf16x8 a_kd[KT], a_qg[K / 32], a_w[K / 32], a_qk; float uu[4];
; #pragma unroll
;     for (int kt = 0; kt < KT; ++kt) {
; #pragma unroll
;         for (int j = 0; j < 4; ++j) S[kt][j] = s0[(size_t)(kt * 16 + 4 * q + j) * 128 + nt * 16 + r]; }
;     if (HASW) { const bf16_t* wb = B.w + un * 64 * 128; const float* ub = B.u + un * 64 * 128;
; #pragma unroll
;         for (int kk = 0; kk < K / 32; ++kk) a_w[kk] = *(const bf16x8*)(wb + r * 128 + kk * 32 + 8 * q);
; #pragma unroll
;         for (int j = 0; j < 4; ++j) uu[j] = ub[(4 * q + j) * 128 + nt * 16 + r]; }
;     else {
; #pragma unroll
;         for (int j = 0; j < 4; ++j) uu[j] = (q == 0) ? vsrc[(size_t)j * LDP + nt * 16 + r] : 0.f; }
; #pragma unroll
;     for (int kk = 0; kk < K / 32; ++kk) a_qg[kk] = *(const bf16x8*)(qg + r * K + kk * 32 + 8 * q);
;     a_qk = *(const bf16x8*)(qk + r * 64 + 8 * q);
; #pragma unroll
;     for (int kt = 0; kt < KT; ++kt) { a_kd[kt] = *(const bf16x8*)(kd + (kt * 16 + r) * 64 + 8 * q); Dr[kt] = *(const f32x4*)(Dv + kt * 16 + 4 * q); }
; DI void scan_short(LAS unsigned char* lds, const Params& P, int l, int T) {
;     const int tid = ltid(), wave = __builtin_amdgcn_readfirstlane(tid >> 6), lane = tid & 63;
;     const int mixer = T / 512, bh = T % 512, b = bh >> 2, h = bh & 3;
;     LAS unsigned char* ldsw = lds + wave * 6144;
;     const float* P32 = (const float*)(lwsp(P) + lo(WS_P32));
;     float* oraw = (float*)(lwsp(P) + lo(WS_ORAW)) + (size_t)mixer * MT * 512 + (size_t)(MPR + b * 4) * 512 + h * 128;
;     const int unit = 512 + bh;
;     if (mixer == 0) { ScanBufs B{(const bf16_t*)(lwsp(P) + lo(PB_QG)), (const bf16_t*)(lwsp(P) + lo(PB_KD)), (const bf16_t*)(lwsp(P) + lo(PB_QK)), (const float*)(lwsp(P) + lo(PB_D)), nullptr, nullptr};
.LBB0_1382:
	s_add_i32 s82, s82, 1
	s_cmp_ge_u32 s82, 3
	s_cbranch_scc1 .LBB0_1412
.LBB0_1383:
	v_readlane_b32 s3, v250, 24
	s_mul_i32 s3, s3, 3
	s_add_i32 s3, s3, s82
	s_addk_i32 s3, 960
	s_mov_b32 s2, 0
	v_mov_b32_e32 v191, v197
	s_or_b32 s15, s2, s3
	s_mov_b64 s[30:31], -1
	v_readfirstlane_b32 s2, v191
	s_ashr_i32 s8, s2, 6
	s_ashr_i32 s2, s15, 31
	s_lshr_b32 s2, s2, 23
	s_add_i32 s2, s15, s2
	s_ashr_i32 s5, s2, 9
	s_and_b32 s2, s2, 0xfffffe00
	s_sub_i32 s14, s15, s2
	s_mul_i32 s2, s8, 0x1800
	s_and_b32 s9, s14, 3
	s_add_i32 s7, s2, 0
	s_mov_b64 s[2:3], 0x10060000
	s_add_u32 s11, s92, s2
	s_addc_u32 s12, s93, s3
	s_mov_b64 s[2:3], 0x30720000
	s_add_u32 s2, s92, s2
	s_addc_u32 s3, s93, s3
	s_mul_hi_i32 s6, s5, 0x1100000
	s_mul_i32 s5, s5, 0x1100000
	s_add_u32 s5, s2, s5
	s_addc_u32 s6, s3, s6
	s_and_b32 s10, s14, -4
	s_add_i32 s28, s10, 0x2000
	s_lshl_b64 s[2:3], s[28:29], 11
	s_add_u32 s2, s5, s2
	s_addc_u32 s3, s6, s3
	s_lshl_b32 s13, s9, 7
	s_lshl_b32 s5, s9, 9
	s_add_u32 s5, s2, s5
	s_addc_u32 s6, s3, 0
	s_add_i32 s2, s14, 0x200
	s_addk_i32 s15, 0x1ff
	v_and_b32_e32 v190, 63, v191
	s_cmpk_gt_u32 s15, 0x3fe
	s_cbranch_scc0 .LBB0_1400
	s_add_i32 s16, s15, 0xfffffe01
	s_and_b32 s16, s16, 0xfffffe00
	s_cmpk_lg_i32 s16, 0x200
	s_cbranch_scc0 .LBB0_1388
	s_mov_b64 s[18:19], 0x2aea0000
	s_add_u32 s17, s92, s18
	s_addc_u32 s18, s93, s19
	s_mov_b64 s[30:31], 0x2bea0000
	s_add_u32 s42, s92, s30
	s_addc_u32 s43, s93, s31
	s_mov_b64 s[30:31], 0x2cea0000
	s_add_u32 s55, s92, s30
	s_addc_u32 s56, s93, s31
	s_mov_b64 s[30:31], 0x2d6a0000
	s_add_u32 s15, s92, s30
	s_addc_u32 s16, s93, s31
	s_mov_b64 s[30:31], 0x2d720000
	s_add_u32 s57, s92, s30
	s_addc_u32 s58, s93, s31
	s_mov_b64 s[30:31], 0x2e720000
	s_add_u32 s19, s92, s30
	s_addc_u32 s54, s93, s31
	s_mov_b64 s[30:31], 0
	v_readlane_b32 s60, v251, 2
	s_lshl_b64 s[30:31], s[30:31], 2
	v_readlane_b32 s68, v251, 10
	v_readlane_b32 s69, v251, 11
	s_add_u32 s3, s68, s30
	s_addc_u32 s44, s69, s31
	s_add_i32 s30, s10, s4
	s_or_b32 s30, s30, s9
	s_ashr_i32 s31, s30, 31
	s_lshl_b64 s[40:41], s[30:31], 16
	v_readlane_b32 s61, v251, 3
	s_add_u32 s59, s3, s40
	s_mov_b32 s3, s29
	s_addc_u32 s61, s44, s41
	s_lshl_b64 s[52:53], s[2:3], 13
	s_lshl_b64 s[50:51], s[2:3], 14
	s_add_u32 s44, s42, s50
	s_addc_u32 s45, s43, s51
	s_lshl_b32 s48, s8, 4
	s_ashr_i32 s49, s48, 31
	s_lshl_b64 s[46:47], s[2:3], 9
	s_lshl_b64 s[42:43], s[48:49], 2
	v_and_b32_e32 v193, 15, v191
	s_add_u32 s60, s59, s42
	v_lshrrev_b32_e32 v8, 4, v190
	s_addc_u32 s61, s61, s43
	v_lshlrev_b32_e32 v0, 2, v193
	v_lshl_add_u64 v[2:3], s[60:61], 0, v[0:1]
	v_lshlrev_b32_e32 v4, 11, v8
	v_mov_b32_e32 v5, v1
	s_mov_b64 s[40:41], 0
	v_lshlrev_b32_e32 v192, 9, v8
	v_lshl_add_u64 v[4:5], v[2:3], 0, v[4:5]
	global_load_dword v100, v[4:5], off
	global_load_dword v101, v[4:5], off offset:512
	global_load_dword v104, v[4:5], off offset:1024
	global_load_dword v105, v[4:5], off offset:1536
	v_or_b32_e32 v4, 0x800, v192
	v_lshlrev_b32_e32 v98, 2, v4
	v_mov_b32_e32 v99, v1
	v_lshl_add_u64 v[4:5], v[2:3], 0, v[98:99]
	global_load_dword v106, v[4:5], off
	v_or_b32_e32 v4, 0x880, v192
	v_lshlrev_b32_e32 v102, 2, v4
	v_mov_b32_e32 v103, v1
	v_lshl_add_u64 v[4:5], v[2:3], 0, v[102:103]
	global_load_dword v107, v[4:5], off
	v_or_b32_e32 v4, 0x900, v192
	v_lshlrev_b32_e32 v108, 2, v4
	v_mov_b32_e32 v109, v1
	v_lshl_add_u64 v[4:5], v[2:3], 0, v[108:109]
	global_load_dword v112, v[4:5], off
	v_or_b32_e32 v4, 0x980, v192
	v_lshlrev_b32_e32 v110, 2, v4
	v_mov_b32_e32 v111, v1
	v_lshl_add_u64 v[4:5], v[2:3], 0, v[110:111]
	global_load_dword v113, v[4:5], off
	v_or_b32_e32 v4, 0x1000, v192
	v_lshlrev_b32_e32 v114, 2, v4
	v_mov_b32_e32 v115, v1
	v_lshl_add_u64 v[4:5], v[2:3], 0, v[114:115]
	global_load_dword v118, v[4:5], off
	v_or_b32_e32 v4, 0x1080, v192
	v_lshlrev_b32_e32 v116, 2, v4
	v_mov_b32_e32 v117, v1
	v_lshl_add_u64 v[4:5], v[2:3], 0, v[116:117]
	global_load_dword v119, v[4:5], off
	v_or_b32_e32 v4, 0x1100, v192
	v_lshlrev_b32_e32 v120, 2, v4
	v_mov_b32_e32 v121, v1
	v_lshl_add_u64 v[4:5], v[2:3], 0, v[120:121]
	global_load_dword v130, v[4:5], off
	v_or_b32_e32 v4, 0x1180, v192
	v_lshlrev_b32_e32 v124, 2, v4
	v_mov_b32_e32 v125, v1
	v_lshl_add_u64 v[4:5], v[2:3], 0, v[124:125]
	global_load_dword v131, v[4:5], off
	v_or_b32_e32 v4, 0x1800, v192
	v_lshlrev_b32_e32 v122, 2, v4
	v_mov_b32_e32 v123, v1
	v_lshl_add_u64 v[4:5], v[2:3], 0, v[122:123]
	global_load_dword v128, v[4:5], off
	v_or_b32_e32 v4, 0x1880, v192
	v_lshlrev_b32_e32 v126, 2, v4
	v_mov_b32_e32 v127, v1
	v_lshl_add_u64 v[4:5], v[2:3], 0, v[126:127]
	global_load_dword v129, v[4:5], off
	v_or_b32_e32 v4, 0x1900, v192
	v_lshlrev_b32_e32 v132, 2, v4
	v_mov_b32_e32 v133, v1
	v_lshl_add_u64 v[4:5], v[2:3], 0, v[132:133]
	global_load_dword v136, v[4:5], off
	v_or_b32_e32 v4, 0x1980, v192
	v_lshlrev_b32_e32 v134, 2, v4
	v_mov_b32_e32 v135, v1
	v_lshl_add_u64 v[4:5], v[2:3], 0, v[134:135]
	global_load_dword v137, v[4:5], off
	v_or_b32_e32 v4, 0x2000, v192
	v_lshlrev_b32_e32 v138, 2, v4
	v_mov_b32_e32 v139, v1
	v_lshl_add_u64 v[4:5], v[2:3], 0, v[138:139]
	global_load_dword v142, v[4:5], off
	v_or_b32_e32 v4, 0x2080, v192
	v_lshlrev_b32_e32 v140, 2, v4
	v_mov_b32_e32 v141, v1
	v_lshl_add_u64 v[4:5], v[2:3], 0, v[140:141]
	global_load_dword v143, v[4:5], off
	v_or_b32_e32 v4, 0x2100, v192
	v_lshlrev_b32_e32 v144, 2, v4
	v_mov_b32_e32 v145, v1
	v_lshl_add_u64 v[4:5], v[2:3], 0, v[144:145]
	global_load_dword v154, v[4:5], off
	v_or_b32_e32 v4, 0x2180, v192
	v_lshlrev_b32_e32 v148, 2, v4
	v_mov_b32_e32 v149, v1
	v_lshl_add_u64 v[4:5], v[2:3], 0, v[148:149]
	global_load_dword v155, v[4:5], off
	v_or_b32_e32 v4, 0x2800, v192
; template <int KT, bool HASW>
; DI void scan_sample_wave(LAS unsigned char* ldsw, const ScanBufs B, int unit, const float* vsrc  , const float* s0, float* sout, float* oraw  , int nt, int lane) {
;     ...
; #pragma unroll
;     for (int kt = 0; kt < KT; ++kt) {
; #pragma unroll
;         for (int j = 0; j < 4; ++j) S[kt][j] = s0[(size_t)(kt * 16 + 4 * q + j) * 128 + nt * 16 + r]; }
;     if (HASW) { const bf16_t* wb = B.w + un * 64 * 128; const float* ub = B.u + un * 64 * 128;
; #pragma unroll
;         for (int kk = 0; kk < K / 32; ++kk) a_w[kk] = *(const bf16x8*)(wb + r * 128 + kk * 32 + 8 * q);
; #pragma unroll
;         for (int j = 0; j < 4; ++j) uu[j] = ub[(4 * q + j) * 128 + nt * 16 + r]; }
;     else {
; #pragma unroll
;         for (int j = 0; j < 4; ++j) uu[j] = (q == 0) ? vsrc[(size_t)j * LDP + nt * 16 + r] : 0.f; }
; #pragma unroll
;     for (int kk = 0; kk < K / 32; ++kk) a_qg[kk] = *(const bf16x8*)(qg + r * K + kk * 32 + 8 * q);
;     a_qk = *(const bf16x8*)(qk + r * 64 + 8 * q);
; #pragma unroll
;     for (int kt = 0; kt < KT; ++kt) { a_kd[kt] = *(const bf16x8*)(kd + (kt * 16 + r) * 64 + 8 * q); Dr[kt] = *(const f32x4*)(Dv + kt * 16 + 4 * q); }
	v_lshlrev_b32_e32 v146, 2, v4
	v_mov_b32_e32 v147, v1
	v_lshl_add_u64 v[4:5], v[2:3], 0, v[146:147]
	global_load_dword v152, v[4:5], off
	v_or_b32_e32 v4, 0x2880, v192
	v_lshlrev_b32_e32 v150, 2, v4
	v_mov_b32_e32 v151, v1
	v_lshl_add_u64 v[4:5], v[2:3], 0, v[150:151]
	global_load_dword v153, v[4:5], off
	v_or_b32_e32 v4, 0x2900, v192
	v_lshlrev_b32_e32 v156, 2, v4
	v_mov_b32_e32 v157, v1
	v_lshl_add_u64 v[4:5], v[2:3], 0, v[156:157]
	global_load_dword v160, v[4:5], off
	v_or_b32_e32 v4, 0x2980, v192
	v_lshlrev_b32_e32 v158, 2, v4
	v_mov_b32_e32 v159, v1
	v_lshl_add_u64 v[4:5], v[2:3], 0, v[158:159]
	global_load_dword v161, v[4:5], off
	v_or_b32_e32 v4, 0x3000, v192
	v_lshlrev_b32_e32 v162, 2, v4
	v_mov_b32_e32 v163, v1
	v_lshl_add_u64 v[4:5], v[2:3], 0, v[162:163]
	global_load_dword v166, v[4:5], off
	v_or_b32_e32 v4, 0x3080, v192
	v_lshlrev_b32_e32 v164, 2, v4
	v_mov_b32_e32 v165, v1
	v_lshl_add_u64 v[4:5], v[2:3], 0, v[164:165]
	global_load_dword v167, v[4:5], off
	v_or_b32_e32 v4, 0x3100, v192
	v_lshlrev_b32_e32 v168, 2, v4
	v_mov_b32_e32 v169, v1
	v_lshl_add_u64 v[4:5], v[2:3], 0, v[168:169]
	global_load_dword v178, v[4:5], off
	v_or_b32_e32 v4, 0x3180, v192
	v_lshlrev_b32_e32 v172, 2, v4
	v_mov_b32_e32 v173, v1
	v_lshl_add_u64 v[4:5], v[2:3], 0, v[172:173]
	global_load_dword v179, v[4:5], off
	v_or_b32_e32 v4, 0x3800, v192
	v_lshlrev_b32_e32 v170, 2, v4
	v_mov_b32_e32 v171, v1
	v_lshl_add_u64 v[4:5], v[2:3], 0, v[170:171]
	global_load_dword v176, v[4:5], off
	v_or_b32_e32 v4, 0x3880, v192
	v_lshlrev_b32_e32 v174, 2, v4
	v_mov_b32_e32 v175, v1
	v_lshl_add_u64 v[4:5], v[2:3], 0, v[174:175]
	global_load_dword v177, v[4:5], off
	v_or_b32_e32 v4, 0x3900, v192
	v_lshlrev_b32_e32 v180, 2, v4
	v_mov_b32_e32 v181, v1
	v_lshl_add_u64 v[4:5], v[2:3], 0, v[180:181]
	global_load_dword v184, v[4:5], off
	v_or_b32_e32 v4, 0x3980, v192
	v_lshlrev_b32_e32 v182, 2, v4
	v_mov_b32_e32 v183, v1
	v_lshl_add_u64 v[2:3], v[2:3], 0, v[182:183]
	global_load_dword v185, v[2:3], off
	s_add_u32 s52, s55, s52
	s_addc_u32 s53, s56, s53
	s_add_u32 s56, s57, s50
	s_addc_u32 s57, s58, s51
	v_lshlrev_b32_e32 v4, 8, v193
	v_mov_b32_e32 v5, v1
	v_lshl_add_u64 v[6:7], s[56:57], 0, v[4:5]
	v_and_b32_e32 v14, 48, v190
	v_mov_b32_e32 v15, v1
	v_lshl_add_u64 v[6:7], v[6:7], 0, v[14:15]
	global_load_dwordx4 v[90:93], v[6:7], off
	global_load_dwordx4 v[206:209], v[6:7], off offset:64
	global_load_dwordx4 v[94:97], v[6:7], off offset:128
	global_load_dwordx4 v[86:89], v[6:7], off offset:192
	s_add_u32 s50, s17, s50
	s_addc_u32 s51, s18, s51
	s_lshl_b64 s[56:57], s[2:3], 15
	v_or_b32_e32 v6, s48, v193
	s_add_u32 s18, s19, s56
	v_add_u32_e32 v6, v6, v192
	s_addc_u32 s19, s54, s57
	v_ashrrev_i32_e32 v7, 31, v6
	v_lshl_add_u64 v[6:7], v[6:7], 2, s[18:19]
	global_load_dword v188, v[6:7], off
	global_load_dword v189, v[6:7], off offset:512
	global_load_dword v186, v[6:7], off offset:1024
	global_load_dword v187, v[6:7], off offset:1536
	v_lshl_add_u64 v[4:5], s[50:51], 0, v[4:5]
	v_lshl_add_u64 v[4:5], v[4:5], 0, v[14:15]
	global_load_dwordx4 v[82:85], v[4:5], off
	global_load_dwordx4 v[78:81], v[4:5], off offset:64
	global_load_dwordx4 v[74:77], v[4:5], off offset:128
	global_load_dwordx4 v[66:69], v[4:5], off offset:192
	v_lshlrev_b32_e32 v2, 7, v193
	v_mov_b32_e32 v3, v1
	v_lshl_add_u64 v[4:5], s[52:53], 0, v[2:3]
	v_lshl_add_u64 v[4:5], v[4:5], 0, v[14:15]
	global_load_dwordx4 v[70:73], v[4:5], off
	v_lshl_add_u64 v[6:7], s[44:45], 0, v[14:15]
	v_lshl_add_u64 v[2:3], v[6:7], 0, v[2:3]
	v_lshlrev_b32_e32 v15, 7, v190
	v_lshlrev_b32_e32 v199, 3, v8
	v_add_co_u32_e32 v4, vcc, s86, v2
	v_or_b32_e32 v8, 0x1800, v15
	v_mov_b32_e32 v9, v1
	s_add_u32 s18, s15, s46
	v_addc_co_u32_e32 v5, vcc, 0, v3, vcc
	v_lshl_add_u64 v[8:9], v[6:7], 0, v[8:9]
	s_addc_u32 s19, s16, s47
	global_load_dwordx4 v[58:61], v[2:3], off
	global_load_dwordx4 v[62:65], v14, s[18:19]
	global_load_dwordx4 v[46:49], v[2:3], off offset:2048
	global_load_dwordx4 v[54:57], v14, s[18:19] offset:64
	global_load_dwordx4 v[34:37], v[4:5], off offset:-4096
	global_load_dwordx4 v[42:45], v14, s[18:19] offset:128
	global_load_dwordx4 v[38:41], v[8:9], off
	global_load_dwordx4 v[50:53], v14, s[18:19] offset:192
	global_load_dwordx4 v[26:29], v[4:5], off
	global_load_dwordx4 v[30:33], v14, s[18:19] offset:256
	global_load_dwordx4 v[18:21], v[4:5], off offset:2048
	global_load_dwordx4 v[22:25], v14, s[18:19] offset:320
	s_movk_i32 s3, 0x3000
	v_add_co_u32_e32 v2, vcc, s3, v2
	v_or_b32_e32 v8, 0x3800, v15
	v_mov_b32_e32 v9, v1
	v_addc_co_u32_e32 v3, vcc, 0, v3, vcc
	v_lshl_add_u64 v[6:7], v[6:7], 0, v[8:9]
	global_load_dwordx4 v[2:5], v[2:3], off
	s_nop 0
	global_load_dwordx4 v[10:13], v14, s[18:19] offset:384
	s_nop 0
	global_load_dwordx4 v[6:9], v[6:7], off
	s_nop 0
	global_load_dwordx4 v[14:17], v14, s[18:19] offset:448
	v_mul_u32_u24_e32 v200, 0x110, v193
	v_add3_u32 v200, s7, v200, v199
	s_waitcnt vmcnt(59)
; #define LAS __attribute__((address_space(3)))
; DI unsigned pk2(float lo, float hi) { const f32x2 v = {lo, hi}; return __builtin_bit_cast(unsigned, __builtin_convertvector(v, bf16n2)); }
; DI f32x4 mfma16(bf16x8 a, bf16x8 b, f32x4 c) { return __builtin_amdgcn_mfma_f32_16x16x32_bf16(a, b, c, 0, 0, 0); }
; template <int KT, bool HASW>
; DI void scan_sample_wave(LAS unsigned char* ldsw, const ScanBufs B, int unit, const float* vsrc  , const float* s0, float* sout, float* oraw  , int nt, int lane) {
;     ...
;     for (int kt = 0; kt < KT; ++kt) { u32x2 w; w.x = pk2(S[kt][0], S[kt][1]); w.y = pk2(S[kt][2], S[kt][3]); *(LAS u32x2*)(ST + r * LDK + kt * 16 + 4 * q) = w; }
;     f32x4 acc = {0.f, 0.f, 0.f, 0.f};
;     if (HASW) {
; #pragma unroll
;         for (int kk = 0; kk < K / 32; ++kk) { const bf16x8 b = *(const LAS bf16x8*)(ST + r * LDK + kk * 32 + 8 * q); acc = mfma16(a_w[kk], b, acc); } }
;     { u32x2 w; w.x = pk2(uu[0] - acc[0], uu[1] - acc[1]); w.y = pk2(uu[2] - acc[2], uu[3] - acc[3]); *(LAS u32x2*)(DT + r * LDD + 4 * q) = w;
;       unsigned vz = 0; asm volatile("" : "+v"(vz)); u32x2 z; z.x = vz; z.y = vz; *(LAS u32x2*)(DT + r * LDD + 16 + 4 * q) = z; }
;     const bf16x8 bd = *(const LAS bf16x8*)(DT + r * LDD + 8 * q);
;     acc = (f32x4){0.f, 0.f, 0.f, 0.f};
; #pragma unroll
;     for (int kk = 0; kk < K / 32; ++kk) { const bf16x8 b = *(const LAS bf16x8*)(ST + r * LDK + kk * 32 + 8 * q); acc = mfma16(a_qg[kk], b, acc); }
;     acc = mfma16(a_qk, bd, acc);
;     if (q == 0) {
; #pragma unroll
;         for (int j = 0; j < 4; ++j) oraw[(size_t)j * 512 + nt * 16 + r] = acc[j]; }
	v_cvt_pk_bf16_f32 v210, v100, v101
	s_waitcnt vmcnt(57)
	v_cvt_pk_bf16_f32 v211, v104, v105
	s_waitcnt vmcnt(55)
	v_cvt_pk_bf16_f32 v212, v106, v107
	s_waitcnt vmcnt(53)
	v_cvt_pk_bf16_f32 v213, v112, v113
	ds_write2_b64 v200, v[210:211], v[212:213] offset1:4
	s_waitcnt vmcnt(51)
	v_cvt_pk_bf16_f32 v210, v118, v119
	s_waitcnt vmcnt(49)
	v_cvt_pk_bf16_f32 v211, v130, v131
	s_waitcnt vmcnt(47)
	v_cvt_pk_bf16_f32 v212, v128, v129
	s_waitcnt vmcnt(45)
	v_cvt_pk_bf16_f32 v213, v136, v137
	ds_write2_b64 v200, v[210:211], v[212:213] offset0:8 offset1:12
	s_waitcnt vmcnt(43)
	v_cvt_pk_bf16_f32 v210, v142, v143
	s_waitcnt vmcnt(41)
	v_cvt_pk_bf16_f32 v211, v154, v155
	s_waitcnt vmcnt(39)
	v_cvt_pk_bf16_f32 v212, v152, v153
	s_waitcnt vmcnt(37)
	v_cvt_pk_bf16_f32 v213, v160, v161
	ds_write2_b64 v200, v[210:211], v[212:213] offset0:16 offset1:20
	s_waitcnt vmcnt(35)
	v_cvt_pk_bf16_f32 v210, v166, v167
	s_waitcnt vmcnt(33)
	v_cvt_pk_bf16_f32 v211, v178, v179
	s_waitcnt vmcnt(31)
	v_cvt_pk_bf16_f32 v212, v176, v177
	v_cmp_gt_u32_e32 vcc, 16, v190
	v_readlane_b32 s62, v251, 4
	v_readlane_b32 s63, v251, 5
	v_readlane_b32 s64, v251, 6
	s_waitcnt vmcnt(29)
	v_cvt_pk_bf16_f32 v213, v184, v185
	ds_write2_b64 v200, v[210:211], v[212:213] offset0:24 offset1:28
	v_add_u32_e32 v200, v200, v199
	ds_read_b128 v[210:213], v200
	s_waitcnt vmcnt(28) lgkmcnt(0)
	v_mfma_f32_16x16x32_bf16 v[90:93], v[90:93], v[210:213], 0
	ds_read_b128 v[210:213], v200 offset:64
	v_readlane_b32 s65, v251, 7
	v_readlane_b32 s66, v251, 8
	s_waitcnt vmcnt(27) lgkmcnt(0)
	v_mfma_f32_16x16x32_bf16 v[90:93], v[206:209], v[210:213], v[90:93]
	ds_read_b128 v[206:209], v200 offset:128
	v_readlane_b32 s67, v251, 9
	v_readlane_b32 s70, v251, 12
	s_waitcnt vmcnt(26) lgkmcnt(0)
	v_mfma_f32_16x16x32_bf16 v[90:93], v[94:97], v[206:209], v[90:93]
	ds_read_b128 v[94:97], v200 offset:192
	v_readlane_b32 s71, v251, 13
	v_readlane_b32 s72, v251, 14
	s_waitcnt vmcnt(25) lgkmcnt(0)
	v_mfma_f32_16x16x32_bf16 v[86:89], v[86:89], v[94:97], v[90:93]
	v_readlane_b32 s73, v251, 15
	v_readlane_b32 s74, v251, 16
	v_readlane_b32 s75, v251, 17
	s_waitcnt vmcnt(23)
	s_nop 3
	v_pk_add_f32 v[86:87], v[188:189], v[86:87] neg_lo:[0,1] neg_hi:[0,1]
	s_waitcnt vmcnt(21)
	v_pk_add_f32 v[88:89], v[186:187], v[88:89] neg_lo:[0,1] neg_hi:[0,1]
	v_cvt_pk_bf16_f32 v86, v86, v87
	v_cvt_pk_bf16_f32 v87, v88, v89
	v_mul_u32_u24_e32 v88, 0x50, v193
	v_add3_u32 v88, s7, v88, v199
	ds_write_b64 v88, v[86:87] offset:4352
	v_mov_b32_e32 v86, v1
	s_nop 0
	v_mov_b32_e32 v87, v86
	ds_write_b64 v88, v[86:87] offset:4384
	v_add_u32_e32 v86, v88, v199
	ds_read_b128 v[86:89], v86 offset:4352
	ds_read_b128 v[90:93], v200
	s_waitcnt vmcnt(20) lgkmcnt(0)
	v_mfma_f32_16x16x32_bf16 v[82:85], v[82:85], v[90:93], 0
	ds_read_b128 v[90:93], v200 offset:64
	s_waitcnt vmcnt(19) lgkmcnt(0)
	v_mfma_f32_16x16x32_bf16 v[78:81], v[78:81], v[90:93], v[82:85]
	s_nop 4
	ds_read_b128 v[82:85], v200 offset:128
	s_waitcnt vmcnt(18) lgkmcnt(0)
	v_mfma_f32_16x16x32_bf16 v[74:77], v[74:77], v[82:85], v[78:81]
	s_nop 2
	ds_read_b128 v[78:81], v200 offset:192
	s_waitcnt vmcnt(17) lgkmcnt(0)
	v_mfma_f32_16x16x32_bf16 v[66:69], v[66:69], v[78:81], v[74:77]
	s_waitcnt vmcnt(16)
	v_mfma_f32_16x16x32_bf16 v[66:69], v[70:73], v[86:89], v[66:69]
	s_and_saveexec_b64 s[44:45], vcc
	s_cbranch_execz .LBB0_1387
	s_add_u32 s16, s5, s42
	s_addc_u32 s17, s6, s43
	v_lshlrev_b32_e32 v70, 2, v190
	v_mov_b32_e32 v71, v1
	v_lshl_add_u64 v[72:73], s[16:17], 0, v[70:71]
	s_nop 0
	global_store_dword v70, v66, s[16:17]
	global_store_dword v70, v67, s[16:17] offset:2048
	v_add_co_u32_e32 v66, vcc, 0x1000, v72
	s_nop 1
	v_addc_co_u32_e32 v67, vcc, 0, v73, vcc
	global_store_dword v[66:67], v68, off
	global_store_dword v[66:67], v69, off offset:2048
